# hand-written epilogues also for GM_OUT x4 and RET_G (all GEMM epilogues now tile-uniform, 16-byte stores)
# baseline (speedup 1.0000x reference)
.LBB0_728:
	v_readfirstlane_b32 s100, v178
	s_nop 0
	s_lshr_b32 s100, s100, 6
	s_lshr_b32 s101, s100, 2
	s_lshl_b32 s101, s101, 7
	s_add_i32 s101, s101, s51
	s_lshl_b32 s101, s101, 11
	s_and_b32 s100, s100, 3
	s_lshl_b32 s100, s100, 6
	s_add_i32 s100, s100, s18
	s_lshl_b32 s100, s100, 1
	s_add_u32 s101, s101, s100
	s_add_u32 s98, s68, s101
	s_addc_u32 s99, s69, 0
	v_and_b32_e32 v242, 15, v178
	v_bfe_u32 v243, v178, 4, 1
	v_lshlrev_b32_e32 v242, 11, v242
	v_lshl_add_u32 v242, v243, 5, v242
	v_bfe_u32 v243, v178, 5, 1
	s_nop 0
	v_lshl_add_u32 v242, v243, 4, v242
	v_cvt_pk_bf16_f32 v124, v124, v125
	v_cvt_pk_bf16_f32 v125, v126, v127
	v_cvt_pk_bf16_f32 v126, v120, v121
	v_cvt_pk_bf16_f32 v127, v122, v123
	v_cvt_pk_bf16_f32 v116, v116, v117
	v_cvt_pk_bf16_f32 v117, v118, v119
	v_cvt_pk_bf16_f32 v118, v112, v113
	v_cvt_pk_bf16_f32 v119, v114, v115
	v_permlane16_swap_b32_e32 v124, v126
	v_permlane16_swap_b32_e32 v125, v127
	v_permlane16_swap_b32_e32 v116, v118
	v_permlane16_swap_b32_e32 v117, v119
	global_store_dwordx4 v242, v[124:127], s[98:99]
	global_store_dwordx4 v242, v[116:119], s[98:99] offset:64
	s_add_u32 s98, s98, 0x8000
	s_addc_u32 s99, s99, 0
	v_cvt_pk_bf16_f32 v108, v108, v109
	v_cvt_pk_bf16_f32 v109, v110, v111
	v_cvt_pk_bf16_f32 v110, v104, v105
	v_cvt_pk_bf16_f32 v111, v106, v107
	v_cvt_pk_bf16_f32 v100, v100, v101
	v_cvt_pk_bf16_f32 v101, v102, v103
	v_cvt_pk_bf16_f32 v102, v96, v97
	v_cvt_pk_bf16_f32 v103, v98, v99
	v_permlane16_swap_b32_e32 v108, v110
	v_permlane16_swap_b32_e32 v109, v111
	v_permlane16_swap_b32_e32 v100, v102
	v_permlane16_swap_b32_e32 v101, v103
	global_store_dwordx4 v242, v[108:111], s[98:99]
	global_store_dwordx4 v242, v[100:103], s[98:99] offset:64
	s_add_u32 s98, s98, 0x8000
	s_addc_u32 s99, s99, 0
	v_cvt_pk_bf16_f32 v92, v92, v93
	v_cvt_pk_bf16_f32 v93, v94, v95
	v_cvt_pk_bf16_f32 v94, v88, v89
	v_cvt_pk_bf16_f32 v95, v90, v91
	v_cvt_pk_bf16_f32 v84, v84, v85
	v_cvt_pk_bf16_f32 v85, v86, v87
	v_cvt_pk_bf16_f32 v86, v80, v81
	v_cvt_pk_bf16_f32 v87, v82, v83
	v_permlane16_swap_b32_e32 v92, v94
	v_permlane16_swap_b32_e32 v93, v95
	v_permlane16_swap_b32_e32 v84, v86
	v_permlane16_swap_b32_e32 v85, v87
	global_store_dwordx4 v242, v[92:95], s[98:99]
	global_store_dwordx4 v242, v[84:87], s[98:99] offset:64
	s_add_u32 s98, s98, 0x8000
	s_addc_u32 s99, s99, 0
	v_cvt_pk_bf16_f32 v76, v76, v77
	v_cvt_pk_bf16_f32 v77, v78, v79
	v_cvt_pk_bf16_f32 v78, v72, v73
	v_cvt_pk_bf16_f32 v79, v74, v75
	v_cvt_pk_bf16_f32 v68, v68, v69
	v_cvt_pk_bf16_f32 v69, v70, v71
	v_cvt_pk_bf16_f32 v70, v64, v65
	v_cvt_pk_bf16_f32 v71, v66, v67
	v_permlane16_swap_b32_e32 v76, v78
	v_permlane16_swap_b32_e32 v77, v79
	v_permlane16_swap_b32_e32 v68, v70
	v_permlane16_swap_b32_e32 v69, v71
	global_store_dwordx4 v242, v[76:79], s[98:99]
	global_store_dwordx4 v242, v[68:71], s[98:99] offset:64
	s_add_u32 s98, s98, 0x8000
	s_addc_u32 s99, s99, 0
	v_cvt_pk_bf16_f32 v60, v60, v61
	v_cvt_pk_bf16_f32 v61, v62, v63
	v_cvt_pk_bf16_f32 v62, v56, v57
	v_cvt_pk_bf16_f32 v63, v58, v59
	v_cvt_pk_bf16_f32 v52, v52, v53
	v_cvt_pk_bf16_f32 v53, v54, v55
	v_cvt_pk_bf16_f32 v54, v48, v49
	v_cvt_pk_bf16_f32 v55, v50, v51
	v_permlane16_swap_b32_e32 v60, v62
	v_permlane16_swap_b32_e32 v61, v63
	v_permlane16_swap_b32_e32 v52, v54
	v_permlane16_swap_b32_e32 v53, v55
	global_store_dwordx4 v242, v[60:63], s[98:99]
	global_store_dwordx4 v242, v[52:55], s[98:99] offset:64
	s_add_u32 s98, s98, 0x8000
	s_addc_u32 s99, s99, 0
	v_cvt_pk_bf16_f32 v44, v44, v45
	v_cvt_pk_bf16_f32 v45, v46, v47
	v_cvt_pk_bf16_f32 v46, v40, v41
	v_cvt_pk_bf16_f32 v47, v42, v43
	v_cvt_pk_bf16_f32 v36, v36, v37
	v_cvt_pk_bf16_f32 v37, v38, v39
	v_cvt_pk_bf16_f32 v38, v32, v33
	v_cvt_pk_bf16_f32 v39, v34, v35
	v_permlane16_swap_b32_e32 v44, v46
	v_permlane16_swap_b32_e32 v45, v47
	v_permlane16_swap_b32_e32 v36, v38
	v_permlane16_swap_b32_e32 v37, v39
	global_store_dwordx4 v242, v[44:47], s[98:99]
	global_store_dwordx4 v242, v[36:39], s[98:99] offset:64
	s_add_u32 s98, s98, 0x8000
	s_addc_u32 s99, s99, 0
	v_cvt_pk_bf16_f32 v28, v28, v29
	v_cvt_pk_bf16_f32 v29, v30, v31
	v_cvt_pk_bf16_f32 v30, v24, v25
	v_cvt_pk_bf16_f32 v31, v26, v27
	v_cvt_pk_bf16_f32 v20, v20, v21
	v_cvt_pk_bf16_f32 v21, v22, v23
	v_cvt_pk_bf16_f32 v22, v16, v17
	v_cvt_pk_bf16_f32 v23, v18, v19
	v_permlane16_swap_b32_e32 v28, v30
	v_permlane16_swap_b32_e32 v29, v31
	v_permlane16_swap_b32_e32 v20, v22
	v_permlane16_swap_b32_e32 v21, v23
	global_store_dwordx4 v242, v[28:31], s[98:99]
	global_store_dwordx4 v242, v[20:23], s[98:99] offset:64
	s_add_u32 s98, s98, 0x8000
	s_addc_u32 s99, s99, 0
	v_cvt_pk_bf16_f32 v12, v12, v13
	v_cvt_pk_bf16_f32 v13, v14, v15
	v_cvt_pk_bf16_f32 v14, v4, v5
	v_cvt_pk_bf16_f32 v15, v6, v7
	v_cvt_pk_bf16_f32 v8, v8, v9
	v_cvt_pk_bf16_f32 v9, v10, v11
	v_cvt_pk_bf16_f32 v10, v0, v1
	v_cvt_pk_bf16_f32 v11, v2, v3
	v_permlane16_swap_b32_e32 v12, v14
	v_permlane16_swap_b32_e32 v13, v15
	v_permlane16_swap_b32_e32 v8, v10
	v_permlane16_swap_b32_e32 v9, v11
	global_store_dwordx4 v242, v[12:15], s[98:99]
	global_store_dwordx4 v242, v[8:11], s[98:99] offset:64
	s_mov_b64 s[26:27], -1
	s_and_b64 vcc, exec, s[16:17]
	s_cbranch_vccnz .LBB0_739

.LBB0_1128:
	v_readfirstlane_b32 s100, v178
	s_nop 0
	s_lshr_b32 s100, s100, 6
	s_lshr_b32 s101, s100, 2
	s_lshl_b32 s101, s101, 7
	s_add_i32 s101, s101, s63
	s_lshl_b32 s101, s101, 12
	s_and_b32 s100, s100, 3
	s_lshl_b32 s100, s100, 6
	s_add_i32 s100, s100, s28
	s_lshl_b32 s100, s100, 1
	s_add_u32 s101, s101, s100
	s_add_u32 s98, s68, s101
	s_addc_u32 s99, s69, 0
	v_and_b32_e32 v242, 15, v178
	v_bfe_u32 v243, v178, 4, 1
	v_lshlrev_b32_e32 v242, 12, v242
	v_lshl_add_u32 v242, v243, 5, v242
	v_bfe_u32 v243, v178, 5, 1
	s_nop 0
	v_lshl_add_u32 v242, v243, 4, v242
	v_mul_f32_e32 v154, 0xbfb8aa3b, v124
	v_mul_f32_e32 v155, 0xbfb8aa3b, v125
	v_mul_f32_e32 v156, 0xbfb8aa3b, v126
	v_mul_f32_e32 v157, 0xbfb8aa3b, v127
	v_exp_f32_e32 v154, v154
	v_exp_f32_e32 v155, v155
	v_exp_f32_e32 v156, v156
	v_exp_f32_e32 v157, v157
	v_add_f32_e32 v154, 1.0, v154
	v_add_f32_e32 v155, 1.0, v155
	v_add_f32_e32 v156, 1.0, v156
	v_add_f32_e32 v157, 1.0, v157
	v_rcp_f32_e32 v154, v154
	v_rcp_f32_e32 v155, v155
	v_rcp_f32_e32 v156, v156
	v_rcp_f32_e32 v157, v157
	v_mul_f32_e32 v124, v124, v154
	v_mul_f32_e32 v125, v125, v155
	v_mul_f32_e32 v126, v126, v156
	v_mul_f32_e32 v127, v127, v157
	v_mul_f32_e32 v158, 0xbfb8aa3b, v120
	v_mul_f32_e32 v159, 0xbfb8aa3b, v121
	v_mul_f32_e32 v160, 0xbfb8aa3b, v122
	v_mul_f32_e32 v161, 0xbfb8aa3b, v123
	v_exp_f32_e32 v158, v158
	v_exp_f32_e32 v159, v159
	v_exp_f32_e32 v160, v160
	v_exp_f32_e32 v161, v161
	v_add_f32_e32 v158, 1.0, v158
	v_add_f32_e32 v159, 1.0, v159
	v_add_f32_e32 v160, 1.0, v160
	v_add_f32_e32 v161, 1.0, v161
	v_rcp_f32_e32 v158, v158
	v_rcp_f32_e32 v159, v159
	v_rcp_f32_e32 v160, v160
	v_rcp_f32_e32 v161, v161
	v_mul_f32_e32 v120, v120, v158
	v_mul_f32_e32 v121, v121, v159
	v_mul_f32_e32 v122, v122, v160
	v_mul_f32_e32 v123, v123, v161
	v_mul_f32_e32 v154, 0xbfb8aa3b, v116
	v_mul_f32_e32 v155, 0xbfb8aa3b, v117
	v_mul_f32_e32 v156, 0xbfb8aa3b, v118
	v_mul_f32_e32 v157, 0xbfb8aa3b, v119
	v_exp_f32_e32 v154, v154
	v_exp_f32_e32 v155, v155
	v_exp_f32_e32 v156, v156
	v_exp_f32_e32 v157, v157
	v_add_f32_e32 v154, 1.0, v154
	v_add_f32_e32 v155, 1.0, v155
	v_add_f32_e32 v156, 1.0, v156
	v_add_f32_e32 v157, 1.0, v157
	v_rcp_f32_e32 v154, v154
	v_rcp_f32_e32 v155, v155
	v_rcp_f32_e32 v156, v156
	v_rcp_f32_e32 v157, v157
	v_mul_f32_e32 v116, v116, v154
	v_mul_f32_e32 v117, v117, v155
	v_mul_f32_e32 v118, v118, v156
	v_mul_f32_e32 v119, v119, v157
	v_mul_f32_e32 v158, 0xbfb8aa3b, v112
	v_mul_f32_e32 v159, 0xbfb8aa3b, v113
	v_mul_f32_e32 v160, 0xbfb8aa3b, v114
	v_mul_f32_e32 v161, 0xbfb8aa3b, v115
	v_exp_f32_e32 v158, v158
	v_exp_f32_e32 v159, v159
	v_exp_f32_e32 v160, v160
	v_exp_f32_e32 v161, v161
	v_add_f32_e32 v158, 1.0, v158
	v_add_f32_e32 v159, 1.0, v159
	v_add_f32_e32 v160, 1.0, v160
	v_add_f32_e32 v161, 1.0, v161
	v_rcp_f32_e32 v158, v158
	v_rcp_f32_e32 v159, v159
	v_rcp_f32_e32 v160, v160
	v_rcp_f32_e32 v161, v161
	v_mul_f32_e32 v112, v112, v158
	v_mul_f32_e32 v113, v113, v159
	v_mul_f32_e32 v114, v114, v160
	v_mul_f32_e32 v115, v115, v161
	v_cvt_pk_bf16_f32 v124, v124, v125
	v_cvt_pk_bf16_f32 v125, v126, v127
	v_cvt_pk_bf16_f32 v126, v120, v121
	v_cvt_pk_bf16_f32 v127, v122, v123
	v_cvt_pk_bf16_f32 v116, v116, v117
	v_cvt_pk_bf16_f32 v117, v118, v119
	v_cvt_pk_bf16_f32 v118, v112, v113
	v_cvt_pk_bf16_f32 v119, v114, v115
	v_permlane16_swap_b32_e32 v124, v126
	v_permlane16_swap_b32_e32 v125, v127
	v_permlane16_swap_b32_e32 v116, v118
	v_permlane16_swap_b32_e32 v117, v119
	global_store_dwordx4 v242, v[124:127], s[98:99]
	global_store_dwordx4 v242, v[116:119], s[98:99] offset:64
	s_add_u32 s98, s98, 0x10000
	s_addc_u32 s99, s99, 0
	v_mul_f32_e32 v154, 0xbfb8aa3b, v108
	v_mul_f32_e32 v155, 0xbfb8aa3b, v109
	v_mul_f32_e32 v156, 0xbfb8aa3b, v110
	v_mul_f32_e32 v157, 0xbfb8aa3b, v111
	v_exp_f32_e32 v154, v154
	v_exp_f32_e32 v155, v155
	v_exp_f32_e32 v156, v156
	v_exp_f32_e32 v157, v157
	v_add_f32_e32 v154, 1.0, v154
	v_add_f32_e32 v155, 1.0, v155
	v_add_f32_e32 v156, 1.0, v156
	v_add_f32_e32 v157, 1.0, v157
	v_rcp_f32_e32 v154, v154
	v_rcp_f32_e32 v155, v155
	v_rcp_f32_e32 v156, v156
	v_rcp_f32_e32 v157, v157
	v_mul_f32_e32 v108, v108, v154
	v_mul_f32_e32 v109, v109, v155
	v_mul_f32_e32 v110, v110, v156
	v_mul_f32_e32 v111, v111, v157
	v_mul_f32_e32 v158, 0xbfb8aa3b, v104
	v_mul_f32_e32 v159, 0xbfb8aa3b, v105
	v_mul_f32_e32 v160, 0xbfb8aa3b, v106
	v_mul_f32_e32 v161, 0xbfb8aa3b, v107
	v_exp_f32_e32 v158, v158
	v_exp_f32_e32 v159, v159
	v_exp_f32_e32 v160, v160
	v_exp_f32_e32 v161, v161
	v_add_f32_e32 v158, 1.0, v158
	v_add_f32_e32 v159, 1.0, v159
	v_add_f32_e32 v160, 1.0, v160
	v_add_f32_e32 v161, 1.0, v161
	v_rcp_f32_e32 v158, v158
	v_rcp_f32_e32 v159, v159
	v_rcp_f32_e32 v160, v160
	v_rcp_f32_e32 v161, v161
	v_mul_f32_e32 v104, v104, v158
	v_mul_f32_e32 v105, v105, v159
	v_mul_f32_e32 v106, v106, v160
	v_mul_f32_e32 v107, v107, v161
	v_mul_f32_e32 v154, 0xbfb8aa3b, v100
	v_mul_f32_e32 v155, 0xbfb8aa3b, v101
	v_mul_f32_e32 v156, 0xbfb8aa3b, v102
	v_mul_f32_e32 v157, 0xbfb8aa3b, v103
	v_exp_f32_e32 v154, v154
	v_exp_f32_e32 v155, v155
	v_exp_f32_e32 v156, v156
	v_exp_f32_e32 v157, v157
	v_add_f32_e32 v154, 1.0, v154
	v_add_f32_e32 v155, 1.0, v155
	v_add_f32_e32 v156, 1.0, v156
	v_add_f32_e32 v157, 1.0, v157
	v_rcp_f32_e32 v154, v154
	v_rcp_f32_e32 v155, v155
	v_rcp_f32_e32 v156, v156
	v_rcp_f32_e32 v157, v157
	v_mul_f32_e32 v100, v100, v154
	v_mul_f32_e32 v101, v101, v155
	v_mul_f32_e32 v102, v102, v156
	v_mul_f32_e32 v103, v103, v157
	v_mul_f32_e32 v158, 0xbfb8aa3b, v96
	v_mul_f32_e32 v159, 0xbfb8aa3b, v97
	v_mul_f32_e32 v160, 0xbfb8aa3b, v98
	v_mul_f32_e32 v161, 0xbfb8aa3b, v99
	v_exp_f32_e32 v158, v158
	v_exp_f32_e32 v159, v159
	v_exp_f32_e32 v160, v160
	v_exp_f32_e32 v161, v161
	v_add_f32_e32 v158, 1.0, v158
	v_add_f32_e32 v159, 1.0, v159
	v_add_f32_e32 v160, 1.0, v160
	v_add_f32_e32 v161, 1.0, v161
	v_rcp_f32_e32 v158, v158
	v_rcp_f32_e32 v159, v159
	v_rcp_f32_e32 v160, v160
	v_rcp_f32_e32 v161, v161
	v_mul_f32_e32 v96, v96, v158
	v_mul_f32_e32 v97, v97, v159
	v_mul_f32_e32 v98, v98, v160
	v_mul_f32_e32 v99, v99, v161
	v_cvt_pk_bf16_f32 v108, v108, v109
	v_cvt_pk_bf16_f32 v109, v110, v111
	v_cvt_pk_bf16_f32 v110, v104, v105
	v_cvt_pk_bf16_f32 v111, v106, v107
	v_cvt_pk_bf16_f32 v100, v100, v101
	v_cvt_pk_bf16_f32 v101, v102, v103
	v_cvt_pk_bf16_f32 v102, v96, v97
	v_cvt_pk_bf16_f32 v103, v98, v99
	v_permlane16_swap_b32_e32 v108, v110
	v_permlane16_swap_b32_e32 v109, v111
	v_permlane16_swap_b32_e32 v100, v102
	v_permlane16_swap_b32_e32 v101, v103
	global_store_dwordx4 v242, v[108:111], s[98:99]
	global_store_dwordx4 v242, v[100:103], s[98:99] offset:64
	s_add_u32 s98, s98, 0x10000
	s_addc_u32 s99, s99, 0
	v_mul_f32_e32 v154, 0xbfb8aa3b, v92
	v_mul_f32_e32 v155, 0xbfb8aa3b, v93
	v_mul_f32_e32 v156, 0xbfb8aa3b, v94
	v_mul_f32_e32 v157, 0xbfb8aa3b, v95
	v_exp_f32_e32 v154, v154
	v_exp_f32_e32 v155, v155
	v_exp_f32_e32 v156, v156
	v_exp_f32_e32 v157, v157
	v_add_f32_e32 v154, 1.0, v154
	v_add_f32_e32 v155, 1.0, v155
	v_add_f32_e32 v156, 1.0, v156
	v_add_f32_e32 v157, 1.0, v157
	v_rcp_f32_e32 v154, v154
	v_rcp_f32_e32 v155, v155
	v_rcp_f32_e32 v156, v156
	v_rcp_f32_e32 v157, v157
	v_mul_f32_e32 v92, v92, v154
	v_mul_f32_e32 v93, v93, v155
	v_mul_f32_e32 v94, v94, v156
	v_mul_f32_e32 v95, v95, v157
	v_mul_f32_e32 v158, 0xbfb8aa3b, v88
	v_mul_f32_e32 v159, 0xbfb8aa3b, v89
	v_mul_f32_e32 v160, 0xbfb8aa3b, v90
	v_mul_f32_e32 v161, 0xbfb8aa3b, v91
	v_exp_f32_e32 v158, v158
	v_exp_f32_e32 v159, v159
	v_exp_f32_e32 v160, v160
	v_exp_f32_e32 v161, v161
	v_add_f32_e32 v158, 1.0, v158
	v_add_f32_e32 v159, 1.0, v159
	v_add_f32_e32 v160, 1.0, v160
	v_add_f32_e32 v161, 1.0, v161
	v_rcp_f32_e32 v158, v158
	v_rcp_f32_e32 v159, v159
	v_rcp_f32_e32 v160, v160
	v_rcp_f32_e32 v161, v161
	v_mul_f32_e32 v88, v88, v158
	v_mul_f32_e32 v89, v89, v159
	v_mul_f32_e32 v90, v90, v160
	v_mul_f32_e32 v91, v91, v161
	v_mul_f32_e32 v154, 0xbfb8aa3b, v84
	v_mul_f32_e32 v155, 0xbfb8aa3b, v85
	v_mul_f32_e32 v156, 0xbfb8aa3b, v86
	v_mul_f32_e32 v157, 0xbfb8aa3b, v87
	v_exp_f32_e32 v154, v154
	v_exp_f32_e32 v155, v155
	v_exp_f32_e32 v156, v156
	v_exp_f32_e32 v157, v157
	v_add_f32_e32 v154, 1.0, v154
	v_add_f32_e32 v155, 1.0, v155
	v_add_f32_e32 v156, 1.0, v156
	v_add_f32_e32 v157, 1.0, v157
	v_rcp_f32_e32 v154, v154
	v_rcp_f32_e32 v155, v155
	v_rcp_f32_e32 v156, v156
	v_rcp_f32_e32 v157, v157
	v_mul_f32_e32 v84, v84, v154
	v_mul_f32_e32 v85, v85, v155
	v_mul_f32_e32 v86, v86, v156
	v_mul_f32_e32 v87, v87, v157
	v_mul_f32_e32 v158, 0xbfb8aa3b, v80
	v_mul_f32_e32 v159, 0xbfb8aa3b, v81
	v_mul_f32_e32 v160, 0xbfb8aa3b, v82
	v_mul_f32_e32 v161, 0xbfb8aa3b, v83
	v_exp_f32_e32 v158, v158
	v_exp_f32_e32 v159, v159
	v_exp_f32_e32 v160, v160
	v_exp_f32_e32 v161, v161
	v_add_f32_e32 v158, 1.0, v158
	v_add_f32_e32 v159, 1.0, v159
	v_add_f32_e32 v160, 1.0, v160
	v_add_f32_e32 v161, 1.0, v161
	v_rcp_f32_e32 v158, v158
	v_rcp_f32_e32 v159, v159
	v_rcp_f32_e32 v160, v160
	v_rcp_f32_e32 v161, v161
	v_mul_f32_e32 v80, v80, v158
	v_mul_f32_e32 v81, v81, v159
	v_mul_f32_e32 v82, v82, v160
	v_mul_f32_e32 v83, v83, v161
	v_cvt_pk_bf16_f32 v92, v92, v93
	v_cvt_pk_bf16_f32 v93, v94, v95
	v_cvt_pk_bf16_f32 v94, v88, v89
	v_cvt_pk_bf16_f32 v95, v90, v91
	v_cvt_pk_bf16_f32 v84, v84, v85
	v_cvt_pk_bf16_f32 v85, v86, v87
	v_cvt_pk_bf16_f32 v86, v80, v81
	v_cvt_pk_bf16_f32 v87, v82, v83
	v_permlane16_swap_b32_e32 v92, v94
	v_permlane16_swap_b32_e32 v93, v95
	v_permlane16_swap_b32_e32 v84, v86
	v_permlane16_swap_b32_e32 v85, v87
	global_store_dwordx4 v242, v[92:95], s[98:99]
	global_store_dwordx4 v242, v[84:87], s[98:99] offset:64
	s_add_u32 s98, s98, 0x10000
	s_addc_u32 s99, s99, 0
	v_mul_f32_e32 v154, 0xbfb8aa3b, v76
	v_mul_f32_e32 v155, 0xbfb8aa3b, v77
	v_mul_f32_e32 v156, 0xbfb8aa3b, v78
	v_mul_f32_e32 v157, 0xbfb8aa3b, v79
	v_exp_f32_e32 v154, v154
	v_exp_f32_e32 v155, v155
	v_exp_f32_e32 v156, v156
	v_exp_f32_e32 v157, v157
	v_add_f32_e32 v154, 1.0, v154
	v_add_f32_e32 v155, 1.0, v155
	v_add_f32_e32 v156, 1.0, v156
	v_add_f32_e32 v157, 1.0, v157
	v_rcp_f32_e32 v154, v154
	v_rcp_f32_e32 v155, v155
	v_rcp_f32_e32 v156, v156
	v_rcp_f32_e32 v157, v157
	v_mul_f32_e32 v76, v76, v154
	v_mul_f32_e32 v77, v77, v155
	v_mul_f32_e32 v78, v78, v156
	v_mul_f32_e32 v79, v79, v157
	v_mul_f32_e32 v158, 0xbfb8aa3b, v72
	v_mul_f32_e32 v159, 0xbfb8aa3b, v73
	v_mul_f32_e32 v160, 0xbfb8aa3b, v74
	v_mul_f32_e32 v161, 0xbfb8aa3b, v75
	v_exp_f32_e32 v158, v158
	v_exp_f32_e32 v159, v159
	v_exp_f32_e32 v160, v160
	v_exp_f32_e32 v161, v161
	v_add_f32_e32 v158, 1.0, v158
	v_add_f32_e32 v159, 1.0, v159
	v_add_f32_e32 v160, 1.0, v160
	v_add_f32_e32 v161, 1.0, v161
	v_rcp_f32_e32 v158, v158
	v_rcp_f32_e32 v159, v159
	v_rcp_f32_e32 v160, v160
	v_rcp_f32_e32 v161, v161
	v_mul_f32_e32 v72, v72, v158
	v_mul_f32_e32 v73, v73, v159
	v_mul_f32_e32 v74, v74, v160
	v_mul_f32_e32 v75, v75, v161
	v_mul_f32_e32 v154, 0xbfb8aa3b, v68
	v_mul_f32_e32 v155, 0xbfb8aa3b, v69
	v_mul_f32_e32 v156, 0xbfb8aa3b, v70
	v_mul_f32_e32 v157, 0xbfb8aa3b, v71
	v_exp_f32_e32 v154, v154
	v_exp_f32_e32 v155, v155
	v_exp_f32_e32 v156, v156
	v_exp_f32_e32 v157, v157
	v_add_f32_e32 v154, 1.0, v154
	v_add_f32_e32 v155, 1.0, v155
	v_add_f32_e32 v156, 1.0, v156
	v_add_f32_e32 v157, 1.0, v157
	v_rcp_f32_e32 v154, v154
	v_rcp_f32_e32 v155, v155
	v_rcp_f32_e32 v156, v156
	v_rcp_f32_e32 v157, v157
	v_mul_f32_e32 v68, v68, v154
	v_mul_f32_e32 v69, v69, v155
	v_mul_f32_e32 v70, v70, v156
	v_mul_f32_e32 v71, v71, v157
	v_mul_f32_e32 v158, 0xbfb8aa3b, v64
	v_mul_f32_e32 v159, 0xbfb8aa3b, v65
	v_mul_f32_e32 v160, 0xbfb8aa3b, v66
	v_mul_f32_e32 v161, 0xbfb8aa3b, v67
	v_exp_f32_e32 v158, v158
	v_exp_f32_e32 v159, v159
	v_exp_f32_e32 v160, v160
	v_exp_f32_e32 v161, v161
	v_add_f32_e32 v158, 1.0, v158
	v_add_f32_e32 v159, 1.0, v159
	v_add_f32_e32 v160, 1.0, v160
	v_add_f32_e32 v161, 1.0, v161
	v_rcp_f32_e32 v158, v158
	v_rcp_f32_e32 v159, v159
	v_rcp_f32_e32 v160, v160
	v_rcp_f32_e32 v161, v161
	v_mul_f32_e32 v64, v64, v158
	v_mul_f32_e32 v65, v65, v159
	v_mul_f32_e32 v66, v66, v160
	v_mul_f32_e32 v67, v67, v161
	v_cvt_pk_bf16_f32 v76, v76, v77
	v_cvt_pk_bf16_f32 v77, v78, v79
	v_cvt_pk_bf16_f32 v78, v72, v73
	v_cvt_pk_bf16_f32 v79, v74, v75
	v_cvt_pk_bf16_f32 v68, v68, v69
	v_cvt_pk_bf16_f32 v69, v70, v71
	v_cvt_pk_bf16_f32 v70, v64, v65
	v_cvt_pk_bf16_f32 v71, v66, v67
	v_permlane16_swap_b32_e32 v76, v78
	v_permlane16_swap_b32_e32 v77, v79
	v_permlane16_swap_b32_e32 v68, v70
	v_permlane16_swap_b32_e32 v69, v71
	global_store_dwordx4 v242, v[76:79], s[98:99]
	global_store_dwordx4 v242, v[68:71], s[98:99] offset:64
	s_add_u32 s98, s98, 0x10000
	s_addc_u32 s99, s99, 0
	v_mul_f32_e32 v154, 0xbfb8aa3b, v60
	v_mul_f32_e32 v155, 0xbfb8aa3b, v61
	v_mul_f32_e32 v156, 0xbfb8aa3b, v62
	v_mul_f32_e32 v157, 0xbfb8aa3b, v63
	v_exp_f32_e32 v154, v154
	v_exp_f32_e32 v155, v155
	v_exp_f32_e32 v156, v156
	v_exp_f32_e32 v157, v157
	v_add_f32_e32 v154, 1.0, v154
	v_add_f32_e32 v155, 1.0, v155
	v_add_f32_e32 v156, 1.0, v156
	v_add_f32_e32 v157, 1.0, v157
	v_rcp_f32_e32 v154, v154
	v_rcp_f32_e32 v155, v155
	v_rcp_f32_e32 v156, v156
	v_rcp_f32_e32 v157, v157
	v_mul_f32_e32 v60, v60, v154
	v_mul_f32_e32 v61, v61, v155
	v_mul_f32_e32 v62, v62, v156
	v_mul_f32_e32 v63, v63, v157
	v_mul_f32_e32 v158, 0xbfb8aa3b, v56
	v_mul_f32_e32 v159, 0xbfb8aa3b, v57
	v_mul_f32_e32 v160, 0xbfb8aa3b, v58
	v_mul_f32_e32 v161, 0xbfb8aa3b, v59
	v_exp_f32_e32 v158, v158
	v_exp_f32_e32 v159, v159
	v_exp_f32_e32 v160, v160
	v_exp_f32_e32 v161, v161
	v_add_f32_e32 v158, 1.0, v158
	v_add_f32_e32 v159, 1.0, v159
	v_add_f32_e32 v160, 1.0, v160
	v_add_f32_e32 v161, 1.0, v161
	v_rcp_f32_e32 v158, v158
	v_rcp_f32_e32 v159, v159
	v_rcp_f32_e32 v160, v160
	v_rcp_f32_e32 v161, v161
	v_mul_f32_e32 v56, v56, v158
	v_mul_f32_e32 v57, v57, v159
	v_mul_f32_e32 v58, v58, v160
	v_mul_f32_e32 v59, v59, v161
	v_mul_f32_e32 v154, 0xbfb8aa3b, v52
	v_mul_f32_e32 v155, 0xbfb8aa3b, v53
	v_mul_f32_e32 v156, 0xbfb8aa3b, v54
	v_mul_f32_e32 v157, 0xbfb8aa3b, v55
	v_exp_f32_e32 v154, v154
	v_exp_f32_e32 v155, v155
	v_exp_f32_e32 v156, v156
	v_exp_f32_e32 v157, v157
	v_add_f32_e32 v154, 1.0, v154
	v_add_f32_e32 v155, 1.0, v155
	v_add_f32_e32 v156, 1.0, v156
	v_add_f32_e32 v157, 1.0, v157
	v_rcp_f32_e32 v154, v154
	v_rcp_f32_e32 v155, v155
	v_rcp_f32_e32 v156, v156
	v_rcp_f32_e32 v157, v157
	v_mul_f32_e32 v52, v52, v154
	v_mul_f32_e32 v53, v53, v155
	v_mul_f32_e32 v54, v54, v156
	v_mul_f32_e32 v55, v55, v157
	v_mul_f32_e32 v158, 0xbfb8aa3b, v48
	v_mul_f32_e32 v159, 0xbfb8aa3b, v49
	v_mul_f32_e32 v160, 0xbfb8aa3b, v50
	v_mul_f32_e32 v161, 0xbfb8aa3b, v51
	v_exp_f32_e32 v158, v158
	v_exp_f32_e32 v159, v159
	v_exp_f32_e32 v160, v160
	v_exp_f32_e32 v161, v161
	v_add_f32_e32 v158, 1.0, v158
	v_add_f32_e32 v159, 1.0, v159
	v_add_f32_e32 v160, 1.0, v160
	v_add_f32_e32 v161, 1.0, v161
	v_rcp_f32_e32 v158, v158
	v_rcp_f32_e32 v159, v159
	v_rcp_f32_e32 v160, v160
	v_rcp_f32_e32 v161, v161
	v_mul_f32_e32 v48, v48, v158
	v_mul_f32_e32 v49, v49, v159
	v_mul_f32_e32 v50, v50, v160
	v_mul_f32_e32 v51, v51, v161
	v_cvt_pk_bf16_f32 v60, v60, v61
	v_cvt_pk_bf16_f32 v61, v62, v63
	v_cvt_pk_bf16_f32 v62, v56, v57
	v_cvt_pk_bf16_f32 v63, v58, v59
	v_cvt_pk_bf16_f32 v52, v52, v53
	v_cvt_pk_bf16_f32 v53, v54, v55
	v_cvt_pk_bf16_f32 v54, v48, v49
	v_cvt_pk_bf16_f32 v55, v50, v51
	v_permlane16_swap_b32_e32 v60, v62
	v_permlane16_swap_b32_e32 v61, v63
	v_permlane16_swap_b32_e32 v52, v54
	v_permlane16_swap_b32_e32 v53, v55
	global_store_dwordx4 v242, v[60:63], s[98:99]
	global_store_dwordx4 v242, v[52:55], s[98:99] offset:64
	s_add_u32 s98, s98, 0x10000
	s_addc_u32 s99, s99, 0
	v_mul_f32_e32 v154, 0xbfb8aa3b, v44
	v_mul_f32_e32 v155, 0xbfb8aa3b, v45
	v_mul_f32_e32 v156, 0xbfb8aa3b, v46
	v_mul_f32_e32 v157, 0xbfb8aa3b, v47
	v_exp_f32_e32 v154, v154
	v_exp_f32_e32 v155, v155
	v_exp_f32_e32 v156, v156
	v_exp_f32_e32 v157, v157
	v_add_f32_e32 v154, 1.0, v154
	v_add_f32_e32 v155, 1.0, v155
	v_add_f32_e32 v156, 1.0, v156
	v_add_f32_e32 v157, 1.0, v157
	v_rcp_f32_e32 v154, v154
	v_rcp_f32_e32 v155, v155
	v_rcp_f32_e32 v156, v156
	v_rcp_f32_e32 v157, v157
	v_mul_f32_e32 v44, v44, v154
	v_mul_f32_e32 v45, v45, v155
	v_mul_f32_e32 v46, v46, v156
	v_mul_f32_e32 v47, v47, v157
	v_mul_f32_e32 v158, 0xbfb8aa3b, v40
	v_mul_f32_e32 v159, 0xbfb8aa3b, v41
	v_mul_f32_e32 v160, 0xbfb8aa3b, v42
	v_mul_f32_e32 v161, 0xbfb8aa3b, v43
	v_exp_f32_e32 v158, v158
	v_exp_f32_e32 v159, v159
	v_exp_f32_e32 v160, v160
	v_exp_f32_e32 v161, v161
	v_add_f32_e32 v158, 1.0, v158
	v_add_f32_e32 v159, 1.0, v159
	v_add_f32_e32 v160, 1.0, v160
	v_add_f32_e32 v161, 1.0, v161
	v_rcp_f32_e32 v158, v158
	v_rcp_f32_e32 v159, v159
	v_rcp_f32_e32 v160, v160
	v_rcp_f32_e32 v161, v161
	v_mul_f32_e32 v40, v40, v158
	v_mul_f32_e32 v41, v41, v159
	v_mul_f32_e32 v42, v42, v160
	v_mul_f32_e32 v43, v43, v161
	v_mul_f32_e32 v154, 0xbfb8aa3b, v36
	v_mul_f32_e32 v155, 0xbfb8aa3b, v37
	v_mul_f32_e32 v156, 0xbfb8aa3b, v38
	v_mul_f32_e32 v157, 0xbfb8aa3b, v39
	v_exp_f32_e32 v154, v154
	v_exp_f32_e32 v155, v155
	v_exp_f32_e32 v156, v156
	v_exp_f32_e32 v157, v157
	v_add_f32_e32 v154, 1.0, v154
	v_add_f32_e32 v155, 1.0, v155
	v_add_f32_e32 v156, 1.0, v156
	v_add_f32_e32 v157, 1.0, v157
	v_rcp_f32_e32 v154, v154
	v_rcp_f32_e32 v155, v155
	v_rcp_f32_e32 v156, v156
	v_rcp_f32_e32 v157, v157
	v_mul_f32_e32 v36, v36, v154
	v_mul_f32_e32 v37, v37, v155
	v_mul_f32_e32 v38, v38, v156
	v_mul_f32_e32 v39, v39, v157
	v_mul_f32_e32 v158, 0xbfb8aa3b, v32
	v_mul_f32_e32 v159, 0xbfb8aa3b, v33
	v_mul_f32_e32 v160, 0xbfb8aa3b, v34
	v_mul_f32_e32 v161, 0xbfb8aa3b, v35
	v_exp_f32_e32 v158, v158
	v_exp_f32_e32 v159, v159
	v_exp_f32_e32 v160, v160
	v_exp_f32_e32 v161, v161
	v_add_f32_e32 v158, 1.0, v158
	v_add_f32_e32 v159, 1.0, v159
	v_add_f32_e32 v160, 1.0, v160
	v_add_f32_e32 v161, 1.0, v161
	v_rcp_f32_e32 v158, v158
	v_rcp_f32_e32 v159, v159
	v_rcp_f32_e32 v160, v160
	v_rcp_f32_e32 v161, v161
	v_mul_f32_e32 v32, v32, v158
	v_mul_f32_e32 v33, v33, v159
	v_mul_f32_e32 v34, v34, v160
	v_mul_f32_e32 v35, v35, v161
	v_cvt_pk_bf16_f32 v44, v44, v45
	v_cvt_pk_bf16_f32 v45, v46, v47
	v_cvt_pk_bf16_f32 v46, v40, v41
	v_cvt_pk_bf16_f32 v47, v42, v43
	v_cvt_pk_bf16_f32 v36, v36, v37
	v_cvt_pk_bf16_f32 v37, v38, v39
	v_cvt_pk_bf16_f32 v38, v32, v33
	v_cvt_pk_bf16_f32 v39, v34, v35
	v_permlane16_swap_b32_e32 v44, v46
	v_permlane16_swap_b32_e32 v45, v47
	v_permlane16_swap_b32_e32 v36, v38
	v_permlane16_swap_b32_e32 v37, v39
	global_store_dwordx4 v242, v[44:47], s[98:99]
	global_store_dwordx4 v242, v[36:39], s[98:99] offset:64
	s_add_u32 s98, s98, 0x10000
	s_addc_u32 s99, s99, 0
	v_mul_f32_e32 v154, 0xbfb8aa3b, v28
	v_mul_f32_e32 v155, 0xbfb8aa3b, v29
	v_mul_f32_e32 v156, 0xbfb8aa3b, v30
	v_mul_f32_e32 v157, 0xbfb8aa3b, v31
	v_exp_f32_e32 v154, v154
	v_exp_f32_e32 v155, v155
	v_exp_f32_e32 v156, v156
	v_exp_f32_e32 v157, v157
	v_add_f32_e32 v154, 1.0, v154
	v_add_f32_e32 v155, 1.0, v155
	v_add_f32_e32 v156, 1.0, v156
	v_add_f32_e32 v157, 1.0, v157
	v_rcp_f32_e32 v154, v154
	v_rcp_f32_e32 v155, v155
	v_rcp_f32_e32 v156, v156
	v_rcp_f32_e32 v157, v157
	v_mul_f32_e32 v28, v28, v154
	v_mul_f32_e32 v29, v29, v155
	v_mul_f32_e32 v30, v30, v156
	v_mul_f32_e32 v31, v31, v157
	v_mul_f32_e32 v158, 0xbfb8aa3b, v24
	v_mul_f32_e32 v159, 0xbfb8aa3b, v25
	v_mul_f32_e32 v160, 0xbfb8aa3b, v26
	v_mul_f32_e32 v161, 0xbfb8aa3b, v27
	v_exp_f32_e32 v158, v158
	v_exp_f32_e32 v159, v159
	v_exp_f32_e32 v160, v160
	v_exp_f32_e32 v161, v161
	v_add_f32_e32 v158, 1.0, v158
	v_add_f32_e32 v159, 1.0, v159
	v_add_f32_e32 v160, 1.0, v160
	v_add_f32_e32 v161, 1.0, v161
	v_rcp_f32_e32 v158, v158
	v_rcp_f32_e32 v159, v159
	v_rcp_f32_e32 v160, v160
	v_rcp_f32_e32 v161, v161
	v_mul_f32_e32 v24, v24, v158
	v_mul_f32_e32 v25, v25, v159
	v_mul_f32_e32 v26, v26, v160
	v_mul_f32_e32 v27, v27, v161
	v_mul_f32_e32 v154, 0xbfb8aa3b, v20
	v_mul_f32_e32 v155, 0xbfb8aa3b, v21
	v_mul_f32_e32 v156, 0xbfb8aa3b, v22
	v_mul_f32_e32 v157, 0xbfb8aa3b, v23
	v_exp_f32_e32 v154, v154
	v_exp_f32_e32 v155, v155
	v_exp_f32_e32 v156, v156
	v_exp_f32_e32 v157, v157
	v_add_f32_e32 v154, 1.0, v154
	v_add_f32_e32 v155, 1.0, v155
	v_add_f32_e32 v156, 1.0, v156
	v_add_f32_e32 v157, 1.0, v157
	v_rcp_f32_e32 v154, v154
	v_rcp_f32_e32 v155, v155
	v_rcp_f32_e32 v156, v156
	v_rcp_f32_e32 v157, v157
	v_mul_f32_e32 v20, v20, v154
	v_mul_f32_e32 v21, v21, v155
	v_mul_f32_e32 v22, v22, v156
	v_mul_f32_e32 v23, v23, v157
	v_mul_f32_e32 v158, 0xbfb8aa3b, v16
	v_mul_f32_e32 v159, 0xbfb8aa3b, v17
	v_mul_f32_e32 v160, 0xbfb8aa3b, v18
	v_mul_f32_e32 v161, 0xbfb8aa3b, v19
	v_exp_f32_e32 v158, v158
	v_exp_f32_e32 v159, v159
	v_exp_f32_e32 v160, v160
	v_exp_f32_e32 v161, v161
	v_add_f32_e32 v158, 1.0, v158
	v_add_f32_e32 v159, 1.0, v159
	v_add_f32_e32 v160, 1.0, v160
	v_add_f32_e32 v161, 1.0, v161
	v_rcp_f32_e32 v158, v158
	v_rcp_f32_e32 v159, v159
	v_rcp_f32_e32 v160, v160
	v_rcp_f32_e32 v161, v161
	v_mul_f32_e32 v16, v16, v158
	v_mul_f32_e32 v17, v17, v159
	v_mul_f32_e32 v18, v18, v160
	v_mul_f32_e32 v19, v19, v161
	v_cvt_pk_bf16_f32 v28, v28, v29
	v_cvt_pk_bf16_f32 v29, v30, v31
	v_cvt_pk_bf16_f32 v30, v24, v25
	v_cvt_pk_bf16_f32 v31, v26, v27
	v_cvt_pk_bf16_f32 v20, v20, v21
	v_cvt_pk_bf16_f32 v21, v22, v23
	v_cvt_pk_bf16_f32 v22, v16, v17
	v_cvt_pk_bf16_f32 v23, v18, v19
	v_permlane16_swap_b32_e32 v28, v30
	v_permlane16_swap_b32_e32 v29, v31
	v_permlane16_swap_b32_e32 v20, v22
	v_permlane16_swap_b32_e32 v21, v23
	global_store_dwordx4 v242, v[28:31], s[98:99]
	global_store_dwordx4 v242, v[20:23], s[98:99] offset:64
	s_add_u32 s98, s98, 0x10000
	s_addc_u32 s99, s99, 0
	v_mul_f32_e32 v154, 0xbfb8aa3b, v12
	v_mul_f32_e32 v155, 0xbfb8aa3b, v13
	v_mul_f32_e32 v156, 0xbfb8aa3b, v14
	v_mul_f32_e32 v157, 0xbfb8aa3b, v15
	v_exp_f32_e32 v154, v154
	v_exp_f32_e32 v155, v155
	v_exp_f32_e32 v156, v156
	v_exp_f32_e32 v157, v157
	v_add_f32_e32 v154, 1.0, v154
	v_add_f32_e32 v155, 1.0, v155
	v_add_f32_e32 v156, 1.0, v156
	v_add_f32_e32 v157, 1.0, v157
	v_rcp_f32_e32 v154, v154
	v_rcp_f32_e32 v155, v155
	v_rcp_f32_e32 v156, v156
	v_rcp_f32_e32 v157, v157
	v_mul_f32_e32 v12, v12, v154
	v_mul_f32_e32 v13, v13, v155
	v_mul_f32_e32 v14, v14, v156
	v_mul_f32_e32 v15, v15, v157
	v_mul_f32_e32 v158, 0xbfb8aa3b, v8
	v_mul_f32_e32 v159, 0xbfb8aa3b, v9
	v_mul_f32_e32 v160, 0xbfb8aa3b, v10
	v_mul_f32_e32 v161, 0xbfb8aa3b, v11
	v_exp_f32_e32 v158, v158
	v_exp_f32_e32 v159, v159
	v_exp_f32_e32 v160, v160
	v_exp_f32_e32 v161, v161
	v_add_f32_e32 v158, 1.0, v158
	v_add_f32_e32 v159, 1.0, v159
	v_add_f32_e32 v160, 1.0, v160
	v_add_f32_e32 v161, 1.0, v161
	v_rcp_f32_e32 v158, v158
	v_rcp_f32_e32 v159, v159
	v_rcp_f32_e32 v160, v160
	v_rcp_f32_e32 v161, v161
	v_mul_f32_e32 v8, v8, v158
	v_mul_f32_e32 v9, v9, v159
	v_mul_f32_e32 v10, v10, v160
	v_mul_f32_e32 v11, v11, v161
	v_mul_f32_e32 v154, 0xbfb8aa3b, v4
	v_mul_f32_e32 v155, 0xbfb8aa3b, v5
	v_mul_f32_e32 v156, 0xbfb8aa3b, v6
	v_mul_f32_e32 v157, 0xbfb8aa3b, v7
	v_exp_f32_e32 v154, v154
	v_exp_f32_e32 v155, v155
	v_exp_f32_e32 v156, v156
	v_exp_f32_e32 v157, v157
	v_add_f32_e32 v154, 1.0, v154
	v_add_f32_e32 v155, 1.0, v155
	v_add_f32_e32 v156, 1.0, v156
	v_add_f32_e32 v157, 1.0, v157
	v_rcp_f32_e32 v154, v154
	v_rcp_f32_e32 v155, v155
	v_rcp_f32_e32 v156, v156
	v_rcp_f32_e32 v157, v157
	v_mul_f32_e32 v4, v4, v154
	v_mul_f32_e32 v5, v5, v155
	v_mul_f32_e32 v6, v6, v156
	v_mul_f32_e32 v7, v7, v157
	v_mul_f32_e32 v158, 0xbfb8aa3b, v0
	v_mul_f32_e32 v159, 0xbfb8aa3b, v1
	v_mul_f32_e32 v160, 0xbfb8aa3b, v2
	v_mul_f32_e32 v161, 0xbfb8aa3b, v3
	v_exp_f32_e32 v158, v158
	v_exp_f32_e32 v159, v159
	v_exp_f32_e32 v160, v160
	v_exp_f32_e32 v161, v161
	v_add_f32_e32 v158, 1.0, v158
	v_add_f32_e32 v159, 1.0, v159
	v_add_f32_e32 v160, 1.0, v160
	v_add_f32_e32 v161, 1.0, v161
	v_rcp_f32_e32 v158, v158
	v_rcp_f32_e32 v159, v159
	v_rcp_f32_e32 v160, v160
	v_rcp_f32_e32 v161, v161
	v_mul_f32_e32 v0, v0, v158
	v_mul_f32_e32 v1, v1, v159
	v_mul_f32_e32 v2, v2, v160
	v_mul_f32_e32 v3, v3, v161
	v_cvt_pk_bf16_f32 v12, v12, v13
	v_cvt_pk_bf16_f32 v13, v14, v15
	v_cvt_pk_bf16_f32 v14, v8, v9
	v_cvt_pk_bf16_f32 v15, v10, v11
	v_cvt_pk_bf16_f32 v4, v4, v5
	v_cvt_pk_bf16_f32 v5, v6, v7
	v_cvt_pk_bf16_f32 v6, v0, v1
	v_cvt_pk_bf16_f32 v7, v2, v3
	v_permlane16_swap_b32_e32 v12, v14
	v_permlane16_swap_b32_e32 v13, v15
	v_permlane16_swap_b32_e32 v4, v6
	v_permlane16_swap_b32_e32 v5, v7
	global_store_dwordx4 v242, v[12:15], s[98:99]
	global_store_dwordx4 v242, v[4:7], s[98:99] offset:64
	s_mov_b64 s[38:39], -1
	s_and_b64 vcc, exec, s[26:27]
	s_cbranch_vccnz .LBB0_1143

.LBB0_1179:
	v_readfirstlane_b32 s100, v178
	s_nop 0
	s_lshr_b32 s100, s100, 6
	s_lshr_b32 s101, s100, 2
	s_lshl_b32 s101, s101, 7
	s_add_i32 s101, s101, s63
	s_lshl_b32 s101, s101, 11
	s_and_b32 s100, s100, 3
	s_lshl_b32 s100, s100, 6
	s_add_i32 s100, s100, s30
	s_lshl_b32 s100, s100, 1
	s_add_u32 s101, s101, s100
	s_add_u32 s98, s4, s101
	s_addc_u32 s99, s5, 0
	v_and_b32_e32 v242, 15, v178
	v_bfe_u32 v243, v178, 4, 1
	v_lshlrev_b32_e32 v242, 11, v242
	v_lshl_add_u32 v242, v243, 5, v242
	v_bfe_u32 v243, v178, 5, 1
	s_nop 0
	v_lshl_add_u32 v242, v243, 4, v242
	v_cvt_pk_bf16_f32 v124, v124, v125
	v_cvt_pk_bf16_f32 v125, v126, v127
	v_cvt_pk_bf16_f32 v126, v120, v121
	v_cvt_pk_bf16_f32 v127, v122, v123
	v_cvt_pk_bf16_f32 v116, v116, v117
	v_cvt_pk_bf16_f32 v117, v118, v119
	v_cvt_pk_bf16_f32 v118, v112, v113
	v_cvt_pk_bf16_f32 v119, v114, v115
	v_permlane16_swap_b32_e32 v124, v126
	v_permlane16_swap_b32_e32 v125, v127
	v_permlane16_swap_b32_e32 v116, v118
	v_permlane16_swap_b32_e32 v117, v119
	global_store_dwordx4 v242, v[124:127], s[98:99]
	global_store_dwordx4 v242, v[116:119], s[98:99] offset:64
	s_add_u32 s98, s98, 0x8000
	s_addc_u32 s99, s99, 0
	v_cvt_pk_bf16_f32 v108, v108, v109
	v_cvt_pk_bf16_f32 v109, v110, v111
	v_cvt_pk_bf16_f32 v110, v104, v105
	v_cvt_pk_bf16_f32 v111, v106, v107
	v_cvt_pk_bf16_f32 v100, v100, v101
	v_cvt_pk_bf16_f32 v101, v102, v103
	v_cvt_pk_bf16_f32 v102, v96, v97
	v_cvt_pk_bf16_f32 v103, v98, v99
	v_permlane16_swap_b32_e32 v108, v110
	v_permlane16_swap_b32_e32 v109, v111
	v_permlane16_swap_b32_e32 v100, v102
	v_permlane16_swap_b32_e32 v101, v103
	global_store_dwordx4 v242, v[108:111], s[98:99]
	global_store_dwordx4 v242, v[100:103], s[98:99] offset:64
	s_add_u32 s98, s98, 0x8000
	s_addc_u32 s99, s99, 0
	v_cvt_pk_bf16_f32 v92, v92, v93
	v_cvt_pk_bf16_f32 v93, v94, v95
	v_cvt_pk_bf16_f32 v94, v88, v89
	v_cvt_pk_bf16_f32 v95, v90, v91
	v_cvt_pk_bf16_f32 v84, v84, v85
	v_cvt_pk_bf16_f32 v85, v86, v87
	v_cvt_pk_bf16_f32 v86, v80, v81
	v_cvt_pk_bf16_f32 v87, v82, v83
	v_permlane16_swap_b32_e32 v92, v94
	v_permlane16_swap_b32_e32 v93, v95
	v_permlane16_swap_b32_e32 v84, v86
	v_permlane16_swap_b32_e32 v85, v87
	global_store_dwordx4 v242, v[92:95], s[98:99]
	global_store_dwordx4 v242, v[84:87], s[98:99] offset:64
	s_add_u32 s98, s98, 0x8000
	s_addc_u32 s99, s99, 0
	v_cvt_pk_bf16_f32 v76, v76, v77
	v_cvt_pk_bf16_f32 v77, v78, v79
	v_cvt_pk_bf16_f32 v78, v72, v73
	v_cvt_pk_bf16_f32 v79, v74, v75
	v_cvt_pk_bf16_f32 v68, v68, v69
	v_cvt_pk_bf16_f32 v69, v70, v71
	v_cvt_pk_bf16_f32 v70, v64, v65
	v_cvt_pk_bf16_f32 v71, v66, v67
	v_permlane16_swap_b32_e32 v76, v78
	v_permlane16_swap_b32_e32 v77, v79
	v_permlane16_swap_b32_e32 v68, v70
	v_permlane16_swap_b32_e32 v69, v71
	global_store_dwordx4 v242, v[76:79], s[98:99]
	global_store_dwordx4 v242, v[68:71], s[98:99] offset:64
	s_add_u32 s98, s98, 0x8000
	s_addc_u32 s99, s99, 0
	v_cvt_pk_bf16_f32 v60, v60, v61
	v_cvt_pk_bf16_f32 v61, v62, v63
	v_cvt_pk_bf16_f32 v62, v56, v57
	v_cvt_pk_bf16_f32 v63, v58, v59
	v_cvt_pk_bf16_f32 v52, v52, v53
	v_cvt_pk_bf16_f32 v53, v54, v55
	v_cvt_pk_bf16_f32 v54, v48, v49
	v_cvt_pk_bf16_f32 v55, v50, v51
	v_permlane16_swap_b32_e32 v60, v62
	v_permlane16_swap_b32_e32 v61, v63
	v_permlane16_swap_b32_e32 v52, v54
	v_permlane16_swap_b32_e32 v53, v55
	global_store_dwordx4 v242, v[60:63], s[98:99]
	global_store_dwordx4 v242, v[52:55], s[98:99] offset:64
	s_add_u32 s98, s98, 0x8000
	s_addc_u32 s99, s99, 0
	v_cvt_pk_bf16_f32 v44, v44, v45
	v_cvt_pk_bf16_f32 v45, v46, v47
	v_cvt_pk_bf16_f32 v46, v40, v41
	v_cvt_pk_bf16_f32 v47, v42, v43
	v_cvt_pk_bf16_f32 v36, v36, v37
	v_cvt_pk_bf16_f32 v37, v38, v39
	v_cvt_pk_bf16_f32 v38, v32, v33
	v_cvt_pk_bf16_f32 v39, v34, v35
	v_permlane16_swap_b32_e32 v44, v46
	v_permlane16_swap_b32_e32 v45, v47
	v_permlane16_swap_b32_e32 v36, v38
	v_permlane16_swap_b32_e32 v37, v39
	global_store_dwordx4 v242, v[44:47], s[98:99]
	global_store_dwordx4 v242, v[36:39], s[98:99] offset:64
	s_add_u32 s98, s98, 0x8000
	s_addc_u32 s99, s99, 0
	v_cvt_pk_bf16_f32 v28, v28, v29
	v_cvt_pk_bf16_f32 v29, v30, v31
	v_cvt_pk_bf16_f32 v30, v24, v25
	v_cvt_pk_bf16_f32 v31, v26, v27
	v_cvt_pk_bf16_f32 v20, v20, v21
	v_cvt_pk_bf16_f32 v21, v22, v23
	v_cvt_pk_bf16_f32 v22, v16, v17
	v_cvt_pk_bf16_f32 v23, v18, v19
	v_permlane16_swap_b32_e32 v28, v30
	v_permlane16_swap_b32_e32 v29, v31
	v_permlane16_swap_b32_e32 v20, v22
	v_permlane16_swap_b32_e32 v21, v23
	global_store_dwordx4 v242, v[28:31], s[98:99]
	global_store_dwordx4 v242, v[20:23], s[98:99] offset:64
	s_add_u32 s98, s98, 0x8000
	s_addc_u32 s99, s99, 0
	v_cvt_pk_bf16_f32 v12, v12, v13
	v_cvt_pk_bf16_f32 v13, v14, v15
	v_cvt_pk_bf16_f32 v14, v4, v5
	v_cvt_pk_bf16_f32 v15, v6, v7
	v_cvt_pk_bf16_f32 v8, v8, v9
	v_cvt_pk_bf16_f32 v9, v10, v11
	v_cvt_pk_bf16_f32 v10, v0, v1
	v_cvt_pk_bf16_f32 v11, v2, v3
	v_permlane16_swap_b32_e32 v12, v14
	v_permlane16_swap_b32_e32 v13, v15
	v_permlane16_swap_b32_e32 v8, v10
	v_permlane16_swap_b32_e32 v9, v11
	global_store_dwordx4 v242, v[12:15], s[98:99]
	global_store_dwordx4 v242, v[8:11], s[98:99] offset:64
	s_mov_b64 s[40:41], -1
	s_and_b64 vcc, exec, s[28:29]
	s_cbranch_vccnz .LBB0_1190

.LBB0_1547:
	v_readfirstlane_b32 s100, v178
	s_nop 0
	s_lshr_b32 s100, s100, 6
	s_lshr_b32 s101, s100, 2
	s_lshl_b32 s101, s101, 7
	s_add_i32 s101, s101, s61
	s_lshl_b32 s101, s101, 11
	s_and_b32 s100, s100, 3
	s_lshl_b32 s100, s100, 6
	s_add_i32 s100, s100, s28
	s_lshl_b32 s100, s100, 1
	s_add_u32 s101, s101, s100
	s_add_u32 s98, s68, s101
	s_addc_u32 s99, s69, 0
	v_and_b32_e32 v242, 15, v178
	v_bfe_u32 v243, v178, 4, 1
	v_lshlrev_b32_e32 v242, 11, v242
	v_lshl_add_u32 v242, v243, 5, v242
	v_bfe_u32 v243, v178, 5, 1
	s_nop 0
	v_lshl_add_u32 v242, v243, 4, v242
	v_cvt_pk_bf16_f32 v124, v124, v125
	v_cvt_pk_bf16_f32 v125, v126, v127
	v_cvt_pk_bf16_f32 v126, v120, v121
	v_cvt_pk_bf16_f32 v127, v122, v123
	v_cvt_pk_bf16_f32 v116, v116, v117
	v_cvt_pk_bf16_f32 v117, v118, v119
	v_cvt_pk_bf16_f32 v118, v112, v113
	v_cvt_pk_bf16_f32 v119, v114, v115
	v_permlane16_swap_b32_e32 v124, v126
	v_permlane16_swap_b32_e32 v125, v127
	v_permlane16_swap_b32_e32 v116, v118
	v_permlane16_swap_b32_e32 v117, v119
	global_store_dwordx4 v242, v[124:127], s[98:99]
	global_store_dwordx4 v242, v[116:119], s[98:99] offset:64
	s_add_u32 s98, s98, 0x8000
	s_addc_u32 s99, s99, 0
	v_cvt_pk_bf16_f32 v108, v108, v109
	v_cvt_pk_bf16_f32 v109, v110, v111
	v_cvt_pk_bf16_f32 v110, v104, v105
	v_cvt_pk_bf16_f32 v111, v106, v107
	v_cvt_pk_bf16_f32 v100, v100, v101
	v_cvt_pk_bf16_f32 v101, v102, v103
	v_cvt_pk_bf16_f32 v102, v96, v97
	v_cvt_pk_bf16_f32 v103, v98, v99
	v_permlane16_swap_b32_e32 v108, v110
	v_permlane16_swap_b32_e32 v109, v111
	v_permlane16_swap_b32_e32 v100, v102
	v_permlane16_swap_b32_e32 v101, v103
	global_store_dwordx4 v242, v[108:111], s[98:99]
	global_store_dwordx4 v242, v[100:103], s[98:99] offset:64
	s_add_u32 s98, s98, 0x8000
	s_addc_u32 s99, s99, 0
	v_cvt_pk_bf16_f32 v92, v92, v93
	v_cvt_pk_bf16_f32 v93, v94, v95
	v_cvt_pk_bf16_f32 v94, v88, v89
	v_cvt_pk_bf16_f32 v95, v90, v91
	v_cvt_pk_bf16_f32 v84, v84, v85
	v_cvt_pk_bf16_f32 v85, v86, v87
	v_cvt_pk_bf16_f32 v86, v80, v81
	v_cvt_pk_bf16_f32 v87, v82, v83
	v_permlane16_swap_b32_e32 v92, v94
	v_permlane16_swap_b32_e32 v93, v95
	v_permlane16_swap_b32_e32 v84, v86
	v_permlane16_swap_b32_e32 v85, v87
	global_store_dwordx4 v242, v[92:95], s[98:99]
	global_store_dwordx4 v242, v[84:87], s[98:99] offset:64
	s_add_u32 s98, s98, 0x8000
	s_addc_u32 s99, s99, 0
	v_cvt_pk_bf16_f32 v76, v76, v77
	v_cvt_pk_bf16_f32 v77, v78, v79
	v_cvt_pk_bf16_f32 v78, v72, v73
	v_cvt_pk_bf16_f32 v79, v74, v75
	v_cvt_pk_bf16_f32 v68, v68, v69
	v_cvt_pk_bf16_f32 v69, v70, v71
	v_cvt_pk_bf16_f32 v70, v64, v65
	v_cvt_pk_bf16_f32 v71, v66, v67
	v_permlane16_swap_b32_e32 v76, v78
	v_permlane16_swap_b32_e32 v77, v79
	v_permlane16_swap_b32_e32 v68, v70
	v_permlane16_swap_b32_e32 v69, v71
	global_store_dwordx4 v242, v[76:79], s[98:99]
	global_store_dwordx4 v242, v[68:71], s[98:99] offset:64
	s_add_u32 s98, s98, 0x8000
	s_addc_u32 s99, s99, 0
	v_cvt_pk_bf16_f32 v60, v60, v61
	v_cvt_pk_bf16_f32 v61, v62, v63
	v_cvt_pk_bf16_f32 v62, v56, v57
	v_cvt_pk_bf16_f32 v63, v58, v59
	v_cvt_pk_bf16_f32 v52, v52, v53
	v_cvt_pk_bf16_f32 v53, v54, v55
	v_cvt_pk_bf16_f32 v54, v48, v49
	v_cvt_pk_bf16_f32 v55, v50, v51
	v_permlane16_swap_b32_e32 v60, v62
	v_permlane16_swap_b32_e32 v61, v63
	v_permlane16_swap_b32_e32 v52, v54
	v_permlane16_swap_b32_e32 v53, v55
	global_store_dwordx4 v242, v[60:63], s[98:99]
	global_store_dwordx4 v242, v[52:55], s[98:99] offset:64
	s_add_u32 s98, s98, 0x8000
	s_addc_u32 s99, s99, 0
	v_cvt_pk_bf16_f32 v44, v44, v45
	v_cvt_pk_bf16_f32 v45, v46, v47
	v_cvt_pk_bf16_f32 v46, v40, v41
	v_cvt_pk_bf16_f32 v47, v42, v43
	v_cvt_pk_bf16_f32 v36, v36, v37
	v_cvt_pk_bf16_f32 v37, v38, v39
	v_cvt_pk_bf16_f32 v38, v32, v33
	v_cvt_pk_bf16_f32 v39, v34, v35
	v_permlane16_swap_b32_e32 v44, v46
	v_permlane16_swap_b32_e32 v45, v47
	v_permlane16_swap_b32_e32 v36, v38
	v_permlane16_swap_b32_e32 v37, v39
	global_store_dwordx4 v242, v[44:47], s[98:99]
	global_store_dwordx4 v242, v[36:39], s[98:99] offset:64
	s_add_u32 s98, s98, 0x8000
	s_addc_u32 s99, s99, 0
	v_cvt_pk_bf16_f32 v28, v28, v29
	v_cvt_pk_bf16_f32 v29, v30, v31
	v_cvt_pk_bf16_f32 v30, v24, v25
	v_cvt_pk_bf16_f32 v31, v26, v27
	v_cvt_pk_bf16_f32 v20, v20, v21
	v_cvt_pk_bf16_f32 v21, v22, v23
	v_cvt_pk_bf16_f32 v22, v16, v17
	v_cvt_pk_bf16_f32 v23, v18, v19
	v_permlane16_swap_b32_e32 v28, v30
	v_permlane16_swap_b32_e32 v29, v31
	v_permlane16_swap_b32_e32 v20, v22
	v_permlane16_swap_b32_e32 v21, v23
	global_store_dwordx4 v242, v[28:31], s[98:99]
	global_store_dwordx4 v242, v[20:23], s[98:99] offset:64
	s_add_u32 s98, s98, 0x8000
	s_addc_u32 s99, s99, 0
	v_cvt_pk_bf16_f32 v12, v12, v13
	v_cvt_pk_bf16_f32 v13, v14, v15
	v_cvt_pk_bf16_f32 v14, v4, v5
	v_cvt_pk_bf16_f32 v15, v6, v7
	v_cvt_pk_bf16_f32 v8, v8, v9
	v_cvt_pk_bf16_f32 v9, v10, v11
	v_cvt_pk_bf16_f32 v10, v0, v1
	v_cvt_pk_bf16_f32 v11, v2, v3
	v_permlane16_swap_b32_e32 v12, v14
	v_permlane16_swap_b32_e32 v13, v15
	v_permlane16_swap_b32_e32 v8, v10
	v_permlane16_swap_b32_e32 v9, v11
	global_store_dwordx4 v242, v[12:15], s[98:99]
	global_store_dwordx4 v242, v[8:11], s[98:99] offset:64
	s_mov_b64 s[38:39], -1
	s_and_b64 vcc, exec, s[26:27]
	s_cbranch_vccnz .LBB0_1558
